# seams 2..5 without L2 maintenance, the skip additionally tied to the token-local P2/P2b mapping being active (otherwise identical to v84)
# speedup vs baseline: 85.0988x; 85.0988x over previous
; __device__ __forceinline__ void own_barrier(unsigned* cnt, unsigned G) {
;     asm volatile("s_waitcnt vmcnt(0) lgkmcnt(0)" ::: "memory");
;     __syncthreads();
;     if (threadIdx.x == 0) {
;         __builtin_amdgcn_fence(__ATOMIC_RELEASE, "agent"); asm volatile("s_waitcnt vmcnt(0)" ::: "memory");
;         unsigned target;
;         if ((G & 7u) == 0u) { target = 8u;
;             const unsigned old = __hip_atomic_fetch_add(cnt + 64 * (1 + (blockIdx.x & 7)), 1u, __ATOMIC_RELAXED, __HIP_MEMORY_SCOPE_AGENT);
;             if (old + 1u == (G >> 3)) __hip_atomic_fetch_add(cnt, 1u, __ATOMIC_RELAXED, __HIP_MEMORY_SCOPE_AGENT); }
;         else { target = G; __hip_atomic_fetch_add(cnt, 1u, __ATOMIC_RELAXED, __HIP_MEMORY_SCOPE_AGENT); }
.LBB0_340:
	s_waitcnt vmcnt(0) lgkmcnt(0)
	s_barrier
	s_mov_b64 s[4:5], exec
	v_readlane_b32 s8, v242, 4
	v_readlane_b32 s9, v242, 5
	s_and_b64 s[8:9], s[4:5], s[8:9]
	s_mov_b64 exec, s[8:9]
	s_cbranch_execz .LBB0_366
	s_cmp_lg_u32 s92, 0x100
	s_cbranch_scc1 .Lseam2_orig
	s_mov_b64 exec, -1
	v_xor_b32_e32 v249, v249, v253
	v_xor_b32_e32 v250, v250, v253
	v_xor_b32_e32 v251, v251, v253
	v_xor_b32_e32 v252, v252, v253
	v_or3_b32 v249, v249, v250, v251
	v_or_b32_e32 v249, v249, v252
	v_readlane_b32 s100, v253, 0
	s_lshl_b32 s100, 1, s100
	s_mov_b32 vcc_lo, s100
	v_readlane_b32 s100, v253, 1
	s_lshl_b32 s100, 1, s100
	s_or_b32 vcc_lo, vcc_lo, s100
	v_readlane_b32 s100, v253, 2
	s_lshl_b32 s100, 1, s100
	s_or_b32 vcc_lo, vcc_lo, s100
	v_readlane_b32 s100, v253, 3
	s_lshl_b32 s100, 1, s100
	s_or_b32 vcc_lo, vcc_lo, s100
	v_readlane_b32 s100, v253, 4
	s_lshl_b32 s100, 1, s100
	s_or_b32 vcc_lo, vcc_lo, s100
	v_readlane_b32 s100, v253, 5
	s_lshl_b32 s100, 1, s100
	s_or_b32 vcc_lo, vcc_lo, s100
	v_readlane_b32 s100, v253, 6
	s_lshl_b32 s100, 1, s100
	s_or_b32 vcc_lo, vcc_lo, s100
	v_readlane_b32 s100, v253, 7
	s_lshl_b32 s100, 1, s100
	s_or_b32 vcc_lo, vcc_lo, s100
	s_cmp_eq_u32 vcc_lo, 0xff
	s_cselect_b32 m0, 1, 0
	v_cmp_ne_u32_e32 vcc, 0, v249
	s_cmp_eq_u64 vcc, 0
	s_cselect_b32 s100, 1, 0
	s_and_b32 s100, s100, m0
	s_cmp_eq_u32 s101, 1
	s_cselect_b32 s100, s100, 0
	s_mov_b64 exec, 1
	v_writelane_b32 v246, s100, 0
	v_readlane_b32 s100, v246, 0
	s_cmp_eq_u32 s100, 1
	s_cbranch_scc1 .Lseam2_nowb
	buffer_wbl2 sc1
	s_waitcnt vmcnt(0)
